# attention main loop unrolled to six steps with static LDS ring bases plus rotated back edge (one taken branch per six tiles, before the barrier)
# speedup vs baseline: 1.0053x; 1.0053x over previous
; __device__ __forceinline__ int otid() { int t = threadIdx.x; asm volatile("" : "+v"(t)); return t; }
; #define WAIT_BAR(N) asm volatile("s_waitcnt vmcnt(" #N ") lgkmcnt(0)\n\ts_barrier":::"memory")
;   #define DMA_K(t,slot) glds16(ksrc+(long)(t)*KVBLK*KVP,(unsigned)__builtin_amdgcn_readfirstlane(kdst+(slot)))
;   #define DMA_V(t,slot) glds16(vsrc+(long)(t)*KVBLK*KVP,(unsigned)__builtin_amdgcn_readfirstlane(vdst+(slot)))
;   #define CMASK(P0,P1,t) do{}while(0)
;   #define CMASK(P0,P1,t) do{}while(0)
;   #define CMASK(P0,P1,t) do{}while(0)
; template<int THRL> __device__ __forceinline__ void attn_unit(const bf16*Qu,const bf16*__restrict__ Kh,const bf16*__restrict__ Vh,bf16*Ou,const int NT,const float shift,char*shm){
;   const int tid=otid(),lane=tid&63,r32=lane&31,hi=lane>>5; const int wid=__builtin_amdgcn_readfirstlane(tid>>6);
;   const bf16*Qw=Qu+(long)wid*QBLK*QP;
;   const unsigned lds0=(unsigned)(uintptr_t)shm;
;   float*wsf=(float*)(shm+LDS_WS)+wid*64;
;   const bf16*ksrc=Kh+(long)lane*KVP+wid*8;
;   const bf16*vsrc=Vh+(long)(16*(wid&3)+(lane>>2))*KVP+(wid>>2)*32+(lane&3)*8;
;   const unsigned kdst=lds0+LDS_K+wid*1024, vdst=lds0+LDS_V+wid*1024;
;     ...
;   const int vb0=(int)(lds0+LDS_V)+((lane>>4)&1)*32+(lane&3)*8+(4*hi+((lane&15)>>2))*64;
;   const char*Kbase=shm+LDS_K; bf16x8 kf[8];
;   const lds_cptr shm3=(lds_cptr)shm; const lds_cptr kp0=shm3+LDS_K+hi*1024+r32*16; const lds_cptr vp0=shm3+LDS_V+((lane>>4)&1)*32+(lane&3)*8+(4*hi+((lane&15)>>2))*64;
;   DMA_K(0,0);DMA_V(0,0);DMA_K(1,SLOTB);
;   bf16x8 qr[4];
;   #pragma unroll
;   for(int d0=0;d0<4;++d0)qr[d0]=*reinterpret_cast<const bf16x8*>(&Qw[(long)r32*QP+d0*16+hi*8]);
;   float mhat=0.f,l_reg=0.f;f32x16 o[2];o[0]=f32x16{};o[1]=f32x16{};f32x16 negm=f32x16{};asm volatile("":"+v"(negm));
;     ...
;   bool resc=false;
;     ...
;   f32x16 pA0,pA1,pB0,pB1;
;   int sl_prev=0,sl_cur=0,sl_next=SLOTB;
;     ...
;   DMA_K(2,2*SLOTB);
;   WAIT_BAR(3);
;   qkt(pA0,pA1,Kbase,qr,negm,r32,hi);asm volatile("s_nop 15\n\ts_nop 7":"+v"(pA0),"+v"(pA1));CMASK(pA0,pA1,0);
;   START(pA0,pA1);
;   _Pragma("unroll") for(int r=0;r<16;++r)pA1[r]=__builtin_amdgcn_exp2f(pA1[r]);
;   WAIT_BAR(0);
.LBB0_616:
	s_lshl_b32 s4, s84, 1
	s_ashr_i32 s5, s82, 2
	s_add_i32 s6, s4, s5
	v_readlane_b32 s4, v246, 62
	v_readlane_b32 s5, v246, 63
	s_lshl_b64 s[4:5], s[4:5], 11
	s_add_u32 s7, s57, s4
	s_addc_u32 s24, s58, s5
	s_lshl_b32 s4, s82, 6
	s_ashr_i32 s5, s4, 31
	s_lshl_b64 s[48:49], s[4:5], 1
	s_add_u32 s26, s7, s48
	s_addc_u32 s27, s24, s49
	s_mul_hi_i32 s7, s6, 0x208000
	s_mul_i32 s6, s6, 0x208000
	s_add_u32 s4, s59, s6
	s_addc_u32 s5, s60, s7
	v_mov_b32_e32 v42, v216
	s_add_u32 s6, s61, s6
	s_addc_u32 s7, s62, s7
	v_readfirstlane_b32 s69, v42
	s_ashr_i32 s44, s69, 6
	s_ashr_i32 s45, s44, 31
	v_and_b32_e32 v238, 63, v42
	s_lshl_b64 s[24:25], s[44:45], 16
	s_add_u32 s24, s26, s24
	v_lshlrev_b32_e32 v0, 4, v42
	s_addc_u32 s25, s27, s25
	v_lshl_add_u64 v[2:3], s[4:5], 0, v[0:1]
	s_mov_b32 s4, 0
	s_ashr_i32 s5, s4, 31
	v_lshl_add_u64 v[212:213], s[4:5], 1, v[2:3]
	s_lshl_b32 s4, s44, 4
	v_bfe_u32 v0, v42, 2, 4
	v_and_or_b32 v0, s4, 48, v0
	s_ashr_i32 s4, s69, 3
	s_andn2_b32 s4, s4, 31
	v_lshlrev_b32_e32 v0, 7, v0
	s_ashr_i32 s5, s4, 31
	s_lshl_b32 s70, s44, 10
	v_lshl_add_u64 v[2:3], s[6:7], 0, v[0:1]
	v_lshlrev_b32_e32 v239, 3, v42
	s_cmp_lg_u32 0, -1
	v_lshl_add_u64 v[2:3], s[4:5], 1, v[2:3]
	v_and_b32_e32 v242, 24, v239
	s_cselect_b32 s4, 0, 0
	v_and_b32_e32 v240, 31, v42
	v_lshlrev_b32_e32 v0, 4, v42
	s_add_i32 s70, s70, s4
	s_mov_b32 s4, m0
	s_mov_b32 m0, s70
	s_nop 0
	global_load_lds_dwordx4 v[212:213], off
	s_mov_b32 m0, s4
	v_bfe_u32 v241, v42, 5, 1
	v_lshl_add_u64 v[214:215], s[6:7], 0, v[0:1]
	s_add_i32 s71, s70, 0x6000
	s_mov_b32 s4, m0
	s_mov_b32 m0, s71
	s_nop 0
	global_load_lds_dwordx4 v[214:215], off
	s_mov_b32 m0, s4
	s_mov_b64 s[26:27], 0x2000
	v_lshlrev_b32_e32 v0, 11, v240
	v_lshl_add_u64 v[2:3], v[212:213], 0, s[26:27]
	s_add_i32 s4, s70, 0x2000
	s_mov_b32 s5, m0
	s_mov_b32 m0, s4
	s_nop 0
	global_load_lds_dwordx4 v[2:3], off
	s_mov_b32 m0, s5
	v_lshl_or_b32 v0, v241, 4, v0
	global_load_dwordx4 v[150:153], v0, s[24:25]
	global_load_dwordx4 v[138:141], v0, s[24:25] offset:32
	global_load_dwordx4 v[134:137], v0, s[24:25] offset:64
	global_load_dwordx4 v[130:133], v0, s[24:25] offset:96
	v_mov_b32_e32 v2, v1
	v_mov_b32_e32 v3, v1
	v_mov_b32_e32 v4, v1
	v_mov_b32_e32 v5, v1
	v_mov_b32_e32 v6, v1
	v_mov_b32_e32 v7, v1
	v_mov_b32_e32 v8, v1
	v_mov_b32_e32 v9, v1
	v_mov_b32_e32 v10, v1
	v_mov_b32_e32 v11, v1
	v_mov_b32_e32 v12, v1
	v_mov_b32_e32 v13, v1
	v_mov_b32_e32 v14, v1
	v_mov_b32_e32 v15, v1
	v_lshlrev_b32_e32 v0, 10, v241
	v_lshlrev_b32_e32 v16, 4, v240
	v_add3_u32 v244, 0, v0, v16
	v_mov_b32_e32 v0, v1
	v_mov_b64_e32 v[16:17], v[14:15]
	v_mov_b64_e32 v[14:15], v[12:13]
	v_mov_b64_e32 v[12:13], v[10:11]
	v_mov_b64_e32 v[10:11], v[8:9]
	v_mov_b64_e32 v[8:9], v[6:7]
	v_mov_b64_e32 v[6:7], v[4:5]
	v_mov_b64_e32 v[4:5], v[2:3]
	v_mov_b64_e32 v[2:3], v[0:1]
	v_lshl_add_u64 v[18:19], v[212:213], 0, s[72:73]
	s_add_i32 s4, s70, 0x4000
	s_mov_b32 s5, m0
	s_mov_b32 m0, s4
	s_nop 0
	global_load_lds_dwordx4 v[18:19], off
	s_mov_b32 m0, s5
	s_waitcnt vmcnt(3) lgkmcnt(0)
	s_barrier
	ds_read_b128 v[34:37], v244
	ds_read_b128 v[38:41], v244 offset:512
	v_lshlrev_b32_e32 v0, 1, v42
	v_and_b32_e32 v243, 32, v0
	s_mov_b64 s[34:35], 0x6000
	v_add_u32_e32 v50, 0, v243
	s_mov_b32 s5, 1
	s_mov_b32 s4, 0
	s_movk_i32 s31, 0x2000
	s_mov_b32 s24, 0
	s_movk_i32 s76, 0x4000
	s_waitcnt vmcnt(3) lgkmcnt(1)
	v_mfma_f32_32x32x16_bf16 v[18:33], v[34:37], v[150:153], v[2:17]
	s_waitcnt lgkmcnt(0)
	v_mfma_f32_32x32x16_bf16 v[2:17], v[38:41], v[150:153], v[2:17]
	ds_read_b128 v[34:37], v244 offset:2048
	ds_read_b128 v[38:41], v244 offset:2560
	s_waitcnt vmcnt(2) lgkmcnt(1)
	v_mfma_f32_32x32x16_bf16 v[18:33], v[34:37], v[138:141], v[18:33]
	s_waitcnt lgkmcnt(0)
	v_mfma_f32_32x32x16_bf16 v[2:17], v[38:41], v[138:141], v[2:17]
	ds_read_b128 v[34:37], v244 offset:4096
	ds_read_b128 v[38:41], v244 offset:4608
	s_waitcnt vmcnt(1) lgkmcnt(1)
	v_mfma_f32_32x32x16_bf16 v[18:33], v[34:37], v[134:137], v[18:33]
	ds_read_b128 v[34:37], v244 offset:6144
	s_waitcnt lgkmcnt(1)
	v_mfma_f32_32x32x16_bf16 v[2:17], v[38:41], v[134:137], v[2:17]
	ds_read_b128 v[38:41], v244 offset:6656
	s_waitcnt vmcnt(0) lgkmcnt(1)
	v_mfma_f32_32x32x16_bf16 v[18:33], v[34:37], v[130:133], v[18:33]
	v_add_f32_e32 v34, v1, v237
	v_lshlrev_b32_e32 v35, 4, v42
	v_xor_b32_e32 v34, 0x80000000, v34
	v_and_b32_e32 v0, 0xc0, v35
	v_mov_b32_e32 v35, v34
	v_mov_b32_e32 v36, v34
	v_mov_b32_e32 v37, v34
	s_waitcnt lgkmcnt(0)
	v_mfma_f32_32x32x16_bf16 v[2:17], v[38:41], v[130:133], v[2:17]
	s_nop 15
	s_nop 7
	v_mov_b32_e32 v38, v34
	v_mov_b32_e32 v39, v34
	v_mov_b32_e32 v40, v34
	v_mov_b32_e32 v41, v34
	v_mov_b32_e32 v42, v34
	v_mov_b32_e32 v43, v34
	v_mov_b32_e32 v44, v34
	v_mov_b32_e32 v45, v34
	v_mov_b32_e32 v46, v34
	v_mov_b32_e32 v47, v34
	v_mov_b32_e32 v48, v34
	v_mov_b32_e32 v49, v34
	v_sub_f32_e32 v2, v2, v237
	v_sub_f32_e32 v3, v3, v237
	s_waitcnt vmcnt(0) lgkmcnt(0)
	s_barrier
; #define WAIT_BAR(N) asm volatile("s_waitcnt vmcnt(" #N ") lgkmcnt(0)\n\ts_barrier":::"memory")
;   #define DMA_K(t,slot) glds16(ksrc+(long)(t)*KVBLK*KVP,(unsigned)__builtin_amdgcn_readfirstlane(kdst+(slot)))
;   #define DMA_V(t,slot) glds16(vsrc+(long)(t)*KVBLK*KVP,(unsigned)__builtin_amdgcn_readfirstlane(vdst+(slot)))
;   #define ROT() do{sl_prev=sl_cur;sl_cur=sl_next;sl_next=(sl_next==(NSLOT-1)*SLOTB)?0:sl_next+SLOTB;}while(0)
; template<int THRL> __device__ __forceinline__ void attn_unit(const bf16*Qu,const bf16*__restrict__ Kh,const bf16*__restrict__ Vh,bf16*Ou,const int NT,const float shift,char*shm){
;     ...
;   _Pragma("unroll") for(int r=0;r<16;++r)pA1[r]=__builtin_amdgcn_exp2f(pA1[r]);
;   WAIT_BAR(0);
;   DMA_K(3,0);DMA_V(1,SLOTB);
;   ROT();
;   kload8(kf,kp0+sl_cur);
;   WAIT_BAR(2);
;     ...
;   int t=1;
;     ...
;   for(;t+5<NT;t+=2){
	v_sub_f32_e32 v18, v18, v237
	v_sub_f32_e32 v19, v19, v237
	s_nop 0
	v_exp_f32_e32 v66, v2
	v_exp_f32_e32 v67, v3
	v_lshl_add_u64 v[2:3], v[212:213], 0, s[34:35]
	s_mov_b32 s6, m0
	s_mov_b32 m0, s70
	s_nop 0
	global_load_lds_dwordx4 v[2:3], off
	s_mov_b32 m0, s6
	v_lshl_add_u64 v[2:3], v[214:215], 0, s[26:27]
	s_add_i32 s6, s70, 0x8000
	s_mov_b32 s7, m0
	s_mov_b32 m0, s6
	s_nop 0
	global_load_lds_dwordx4 v[2:3], off
	s_mov_b32 m0, s7
	ds_read_b128 v[190:193], v244 offset:8192
	ds_read_b128 v[186:189], v244 offset:8704
	ds_read_b128 v[182:185], v244 offset:10240
	ds_read_b128 v[178:181], v244 offset:10752
	ds_read_b128 v[174:177], v244 offset:12288
	ds_read_b128 v[170:173], v244 offset:12800
	ds_read_b128 v[166:169], v244 offset:14336
	ds_read_b128 v[162:165], v244 offset:14848
	v_sub_f32_e32 v20, v20, v237
	v_sub_f32_e32 v4, v4, v237
	v_sub_f32_e32 v21, v21, v237
	v_sub_f32_e32 v5, v5, v237
	v_sub_f32_e32 v22, v22, v237
	v_sub_f32_e32 v6, v6, v237
	v_sub_f32_e32 v23, v23, v237
	v_sub_f32_e32 v7, v7, v237
	v_sub_f32_e32 v24, v24, v237
	v_sub_f32_e32 v8, v8, v237
	v_sub_f32_e32 v25, v25, v237
	v_sub_f32_e32 v9, v9, v237
	v_sub_f32_e32 v26, v26, v237
	v_sub_f32_e32 v10, v10, v237
	v_sub_f32_e32 v27, v27, v237
	v_sub_f32_e32 v11, v11, v237
	v_sub_f32_e32 v28, v28, v237
	v_sub_f32_e32 v12, v12, v237
	v_sub_f32_e32 v29, v29, v237
	v_sub_f32_e32 v13, v13, v237
	v_sub_f32_e32 v30, v30, v237
	v_sub_f32_e32 v14, v14, v237
	v_sub_f32_e32 v31, v31, v237
	v_sub_f32_e32 v15, v15, v237
	v_sub_f32_e32 v32, v32, v237
	v_sub_f32_e32 v16, v16, v237
	v_sub_f32_e32 v33, v33, v237
	v_sub_f32_e32 v17, v17, v237
	v_exp_f32_e32 v82, v18
	v_exp_f32_e32 v83, v19
	v_exp_f32_e32 v84, v20
	v_exp_f32_e32 v85, v21
	v_exp_f32_e32 v86, v22
	v_exp_f32_e32 v87, v23
	v_exp_f32_e32 v88, v24
	v_exp_f32_e32 v89, v25
	v_exp_f32_e32 v90, v26
	v_exp_f32_e32 v91, v27
	v_exp_f32_e32 v92, v28
	v_exp_f32_e32 v93, v29
	v_exp_f32_e32 v94, v30
	v_exp_f32_e32 v95, v31
	v_exp_f32_e32 v96, v32
	v_exp_f32_e32 v97, v33
	v_exp_f32_e32 v68, v4
	v_exp_f32_e32 v69, v5
	v_exp_f32_e32 v70, v6
	v_exp_f32_e32 v71, v7
	v_exp_f32_e32 v72, v8
	v_exp_f32_e32 v73, v9
	v_exp_f32_e32 v74, v10
	v_exp_f32_e32 v75, v11
	v_exp_f32_e32 v76, v12
	v_exp_f32_e32 v77, v13
	v_exp_f32_e32 v78, v14
	v_exp_f32_e32 v79, v15
	v_exp_f32_e32 v80, v16
	v_exp_f32_e32 v81, v17
	s_waitcnt vmcnt(2) lgkmcnt(0)
	s_barrier
	v_lshl_or_b32 v0, v241, 8, v0
	v_add3_u32 v245, v50, v242, v0
	s_cmp_lt_i32 s91, 7
	s_cbranch_scc1 .LBB0_620
	s_mov_b64 s[4:5], 0xa000
	v_mov_b32_e32 v199, v245
	v_add_u32_e32 v200, 0x2000, v245
	v_add_u32_e32 v201, 0x4000, v245
	v_mov_b32_e32 v202, v244
	v_add_u32_e32 v203, 0x2000, v244
	v_add_u32_e32 v204, 0x4000, v244
	v_mov_b32_e32 v50, 0
	v_mov_b32_e32 v194, 0
	v_mov_b32_e32 v195, 0
	v_mov_b32_e32 v196, 0
	v_lshlrev_b32_e32 v197, 4, v238
	v_readfirstlane_b32 s98, v212
	v_readfirstlane_b32 s99, v213
	v_readfirstlane_b32 s100, v214
	v_readfirstlane_b32 s101, v215
	s_add_u32 s98, s98, 0x8000
	s_addc_u32 s99, s99, 0
	s_add_u32 s100, s100, 0x4000
	s_addc_u32 s101, s101, 0
	s_mov_b32 s26, 6
	v_mov_b32_e32 v2, 0
	v_mov_b32_e32 v3, v50
	v_mov_b32_e32 v4, v50
	v_mov_b32_e32 v5, v50
	v_mov_b32_e32 v6, v50
	v_mov_b32_e32 v7, v50
	v_mov_b32_e32 v8, v50
	v_mov_b32_e32 v9, v50
	v_mov_b32_e32 v10, v50
	v_mov_b32_e32 v11, v50
	v_mov_b32_e32 v12, v50
	v_mov_b32_e32 v13, v50
	v_mov_b32_e32 v14, v50
	v_mov_b32_e32 v15, v50
	v_mov_b32_e32 v16, v50
	v_mov_b32_e32 v17, v50
	v_mov_b32_e32 v18, 0
	v_mov_b32_e32 v19, v50
	v_mov_b32_e32 v20, v50
	v_mov_b32_e32 v21, v50
	v_mov_b32_e32 v22, v50
	v_mov_b32_e32 v23, v50
	v_mov_b32_e32 v24, v50
	v_mov_b32_e32 v25, v50
	v_mov_b32_e32 v26, v50
	v_mov_b32_e32 v27, v50
	v_mov_b32_e32 v28, v50
	v_mov_b32_e32 v29, v50
	v_mov_b32_e32 v30, v50
	v_mov_b32_e32 v31, v50
	v_mov_b32_e32 v32, v50
	v_mov_b32_e32 v33, v50
	s_branch .LBB0_618

; #define WAIT_BAR(N) asm volatile("s_waitcnt vmcnt(" #N ") lgkmcnt(0)\n\ts_barrier":::"memory")
;   #define RESC() do{ if(resc){ asm volatile("s_waitcnt lgkmcnt(0)":::"memory"); \
;       _Pragma("unroll") for(int d_=0;d_<2;++d_) _Pragma("unroll") for(int r=0;r<16;++r)o[d_][r]*=wsf[crow(r,hi)]; } }while(0)
;   #define ROT() do{sl_prev=sl_cur;sl_cur=sl_next;sl_next=(sl_next==(NSLOT-1)*SLOTB)?0:sl_next+SLOTB;}while(0)
; template<int THRL> __device__ __forceinline__ void attn_unit(const bf16*Qu,const bf16*__restrict__ Kh,const bf16*__restrict__ Vh,bf16*Ou,const int NT,const float shift,char*shm){
;     ...
;   int t=1;
;     ...
;   for(;t+5<NT;t+=2){
;     STEP(pB0,pB1,pA0,pA1,t,true,true,true);     WAIT_BAR(2); RESC(); ROT();
;     STEP(pA0,pA1,pB0,pB1,t+1,true,true,true);   WAIT_BAR(2); RESC(); ROT();
.LBB0_618:
	s_mov_b32 s4, s76
	s_mov_b32 s5, s26
	s_mov_b32 s25, s31
	ds_read_b64_tr_b16 v[52:53], v199 offset:24576
	ds_read_b64_tr_b16 v[54:55], v199 offset:25088
	s_waitcnt lgkmcnt(9)
	v_mfma_f32_32x32x16_bf16 v[114:129], v[190:193], v[150:153], v[34:49]
	v_add_f32_e32 v50, v82, v50
	v_add_f32_e32 v194, v83, v194
	v_add_f32_e32 v195, v84, v195
	v_add_f32_e32 v196, v85, v196
	v_add_f32_e32 v50, v86, v50
	v_add_f32_e32 v194, v87, v194
	v_cvt_pk_bf16_f32 v158, v82, v83
	v_cvt_pk_bf16_f32 v159, v84, v85
	ds_read_b64_tr_b16 v[60:61], v199 offset:28672
	ds_read_b64_tr_b16 v[62:63], v199 offset:29184
	s_waitcnt lgkmcnt(10)
	v_mfma_f32_32x32x16_bf16 v[98:113], v[186:189], v[150:153], v[34:49]
	v_add_f32_e32 v195, v88, v195
	v_add_f32_e32 v196, v89, v196
	v_add_f32_e32 v50, v90, v50
	v_add_f32_e32 v194, v91, v194
	v_cvt_pk_bf16_f32 v160, v86, v87
	v_cvt_pk_bf16_f32 v161, v88, v89
	ds_read_b64_tr_b16 v[82:83], v199 offset:25600
	ds_read_b64_tr_b16 v[84:85], v199 offset:26112
	s_waitcnt lgkmcnt(11)
	v_mfma_f32_32x32x16_bf16 v[114:129], v[182:185], v[138:141], v[114:129]
	v_add_f32_e32 v195, v92, v195
	v_add_f32_e32 v196, v93, v196
	v_add_f32_e32 v50, v94, v50
	v_add_f32_e32 v194, v95, v194
	v_cvt_pk_bf16_f32 v154, v90, v91
	v_cvt_pk_bf16_f32 v155, v92, v93
	ds_read_b64_tr_b16 v[86:87], v199 offset:29696
	ds_read_b64_tr_b16 v[88:89], v199 offset:30208
	s_waitcnt lgkmcnt(12)
	v_mfma_f32_32x32x16_bf16 v[98:113], v[178:181], v[138:141], v[98:113]
	v_add_f32_e32 v195, v96, v195
	v_add_f32_e32 v196, v97, v196
	v_add_f32_e32 v50, v66, v50
	v_add_f32_e32 v194, v67, v194
	v_cvt_pk_bf16_f32 v156, v94, v95
	v_cvt_pk_bf16_f32 v157, v96, v97
	ds_read_b64_tr_b16 v[90:91], v199 offset:26624
	ds_read_b64_tr_b16 v[92:93], v199 offset:27136
	s_waitcnt lgkmcnt(13)
	v_mfma_f32_32x32x16_bf16 v[114:129], v[174:177], v[134:137], v[114:129]
	v_add_f32_e32 v195, v68, v195
	v_add_f32_e32 v196, v69, v196
	v_add_f32_e32 v50, v70, v50
	v_add_f32_e32 v194, v71, v194
	v_cvt_pk_bf16_f32 v146, v66, v67
	v_cvt_pk_bf16_f32 v147, v68, v69
	ds_read_b64_tr_b16 v[64:65], v199 offset:30720
	ds_read_b64_tr_b16 v[66:67], v199 offset:31232
	s_waitcnt lgkmcnt(14)
	v_mfma_f32_32x32x16_bf16 v[98:113], v[170:173], v[134:137], v[98:113]
	v_add_f32_e32 v195, v72, v195
	v_add_f32_e32 v196, v73, v196
	v_add_f32_e32 v50, v74, v50
	v_add_f32_e32 v194, v75, v194
	v_cvt_pk_bf16_f32 v148, v70, v71
	v_cvt_pk_bf16_f32 v149, v72, v73
	ds_read_b64_tr_b16 v[68:69], v199 offset:27648
	ds_read_b64_tr_b16 v[70:71], v199 offset:28160
	s_waitcnt lgkmcnt(14)
	v_mfma_f32_32x32x16_bf16 v[114:129], v[166:169], v[130:133], v[114:129]
	v_add_f32_e32 v195, v76, v195
	v_add_f32_e32 v196, v77, v196
	v_add_f32_e32 v50, v78, v50
	v_add_f32_e32 v194, v79, v194
	v_cvt_pk_bf16_f32 v142, v74, v75
	v_cvt_pk_bf16_f32 v143, v76, v77
	ds_read_b64_tr_b16 v[72:73], v199 offset:31744
	ds_read_b64_tr_b16 v[74:75], v199 offset:32256
	v_mfma_f32_32x32x16_bf16 v[98:113], v[162:165], v[130:133], v[98:113]
	v_add_f32_e32 v195, v80, v195
	v_add_f32_e32 v196, v81, v196
	v_cvt_pk_bf16_f32 v144, v78, v79
	v_cvt_pk_bf16_f32 v145, v80, v81
	s_add_i32 s6, s31, s70
	s_mov_b32 s7, m0
	s_mov_b32 m0, s6
	s_nop 0
	global_load_lds_dwordx4 v197, s[98:99]
	s_mov_b32 m0, s7
	s_add_i32 s6, s76, s71
	s_mov_b32 s7, m0
	s_mov_b32 m0, s6
	s_nop 0
	global_load_lds_dwordx4 v197, s[100:101]
	s_mov_b32 m0, s7
	s_add_u32 s98, s98, 0x2000
	s_addc_u32 s99, s99, 0
	s_add_u32 s100, s100, 0x2000
	s_addc_u32 s101, s101, 0
	s_waitcnt lgkmcnt(14)
	v_mfma_f32_32x32x16_bf16 v[2:17], v[158:161], v[52:55], v[2:17]
	v_exp_f32_e32 v114, v114
	v_exp_f32_e32 v115, v115
	v_exp_f32_e32 v116, v116
	v_exp_f32_e32 v117, v117
	s_waitcnt lgkmcnt(12)
	v_mfma_f32_32x32x16_bf16 v[18:33], v[158:161], v[60:63], v[18:33]
	v_exp_f32_e32 v118, v118
	v_exp_f32_e32 v119, v119
	v_exp_f32_e32 v120, v120
	v_exp_f32_e32 v121, v121
	ds_read_b128 v[60:63], v204
	ds_read_b128 v[162:165], v204 offset:512
	s_waitcnt lgkmcnt(12)
	v_mfma_f32_32x32x16_bf16 v[2:17], v[154:157], v[82:85], v[2:17]
	v_exp_f32_e32 v122, v122
	v_exp_f32_e32 v123, v123
	v_exp_f32_e32 v124, v124
	v_exp_f32_e32 v125, v125
	ds_read_b128 v[166:169], v204 offset:2048
	ds_read_b128 v[170:173], v204 offset:2560
	s_waitcnt lgkmcnt(12)
	v_mfma_f32_32x32x16_bf16 v[18:33], v[154:157], v[86:89], v[18:33]
	v_exp_f32_e32 v126, v126
	v_exp_f32_e32 v127, v127
	v_exp_f32_e32 v128, v128
	v_exp_f32_e32 v129, v129
	ds_read_b128 v[174:177], v204 offset:4096
	ds_read_b128 v[178:181], v204 offset:4608
	s_waitcnt lgkmcnt(12)
	v_mfma_f32_32x32x16_bf16 v[2:17], v[146:149], v[90:93], v[2:17]
	v_exp_f32_e32 v98, v98
	v_exp_f32_e32 v99, v99
	v_exp_f32_e32 v100, v100
	v_exp_f32_e32 v101, v101
	ds_read_b128 v[182:185], v204 offset:6144
	ds_read_b128 v[52:55], v204 offset:6656
	s_waitcnt lgkmcnt(12)
	v_mfma_f32_32x32x16_bf16 v[18:33], v[146:149], v[64:67], v[18:33]
	v_exp_f32_e32 v102, v102
	v_exp_f32_e32 v103, v103
	v_exp_f32_e32 v104, v104
	v_exp_f32_e32 v105, v105
	s_waitcnt lgkmcnt(10)
	v_mfma_f32_32x32x16_bf16 v[2:17], v[142:145], v[68:71], v[2:17]
	v_exp_f32_e32 v106, v106
	v_exp_f32_e32 v107, v107
	v_exp_f32_e32 v108, v108
	v_exp_f32_e32 v109, v109
	s_waitcnt lgkmcnt(8)
	v_mfma_f32_32x32x16_bf16 v[18:33], v[142:145], v[72:75], v[18:33]
	v_exp_f32_e32 v110, v110
	v_exp_f32_e32 v111, v111
	v_exp_f32_e32 v112, v112
	v_exp_f32_e32 v113, v113
	s_waitcnt vmcnt(2) lgkmcnt(0)
	s_barrier
; #define WAIT_BAR(N) asm volatile("s_waitcnt vmcnt(" #N ") lgkmcnt(0)\n\ts_barrier":::"memory")
;   #define RESC() do{ if(resc){ asm volatile("s_waitcnt lgkmcnt(0)":::"memory"); \
;       _Pragma("unroll") for(int d_=0;d_<2;++d_) _Pragma("unroll") for(int r=0;r<16;++r)o[d_][r]*=wsf[crow(r,hi)]; } }while(0)
;   #define ROT() do{sl_prev=sl_cur;sl_cur=sl_next;sl_next=(sl_next==(NSLOT-1)*SLOTB)?0:sl_next+SLOTB;}while(0)
; template<int THRL> __device__ __forceinline__ void attn_unit(const bf16*Qu,const bf16*__restrict__ Kh,const bf16*__restrict__ Vh,bf16*Ou,const int NT,const float shift,char*shm){
;     ...
;   int t=1;
;     ...
;   for(;t+5<NT;t+=2){
;     STEP(pB0,pB1,pA0,pA1,t,true,true,true);     WAIT_BAR(2); RESC(); ROT();
;     STEP(pA0,pA1,pB0,pB1,t+1,true,true,true);   WAIT_BAR(2); RESC(); ROT();
;   }
	s_add_i32 s6, s76, 0x2000
	s_cmpk_lg_i32 s76, 0x4000
	s_cselect_b32 s31, s6, 0
	ds_read_b64_tr_b16 v[186:187], v200 offset:24576
	ds_read_b64_tr_b16 v[188:189], v200 offset:25088
	s_waitcnt lgkmcnt(9)
	v_mfma_f32_32x32x16_bf16 v[82:97], v[60:63], v[150:153], v[34:49]
	v_add_f32_e32 v50, v114, v50
	v_add_f32_e32 v194, v115, v194
	v_add_f32_e32 v195, v116, v195
	v_add_f32_e32 v196, v117, v196
	v_add_f32_e32 v50, v118, v50
	v_add_f32_e32 v194, v119, v194
	v_cvt_pk_bf16_f32 v158, v114, v115
	v_cvt_pk_bf16_f32 v159, v116, v117
	ds_read_b64_tr_b16 v[60:61], v200 offset:28672
	ds_read_b64_tr_b16 v[62:63], v200 offset:29184
	s_waitcnt lgkmcnt(10)
	v_mfma_f32_32x32x16_bf16 v[66:81], v[162:165], v[150:153], v[34:49]
	v_add_f32_e32 v195, v120, v195
	v_add_f32_e32 v196, v121, v196
	v_add_f32_e32 v50, v122, v50
	v_add_f32_e32 v194, v123, v194
	v_cvt_pk_bf16_f32 v160, v118, v119
	v_cvt_pk_bf16_f32 v161, v120, v121
	ds_read_b64_tr_b16 v[114:115], v200 offset:25600
	ds_read_b64_tr_b16 v[116:117], v200 offset:26112
	s_waitcnt lgkmcnt(11)
	v_mfma_f32_32x32x16_bf16 v[82:97], v[166:169], v[138:141], v[82:97]
	v_add_f32_e32 v195, v124, v195
	v_add_f32_e32 v196, v125, v196
	v_add_f32_e32 v50, v126, v50
	v_add_f32_e32 v194, v127, v194
	v_cvt_pk_bf16_f32 v154, v122, v123
	v_cvt_pk_bf16_f32 v155, v124, v125
	ds_read_b64_tr_b16 v[118:119], v200 offset:29696
	ds_read_b64_tr_b16 v[120:121], v200 offset:30208
	s_waitcnt lgkmcnt(12)
	v_mfma_f32_32x32x16_bf16 v[66:81], v[170:173], v[138:141], v[66:81]
	v_add_f32_e32 v195, v128, v195
	v_add_f32_e32 v196, v129, v196
	v_add_f32_e32 v50, v98, v50
	v_add_f32_e32 v194, v99, v194
	v_cvt_pk_bf16_f32 v156, v126, v127
	v_cvt_pk_bf16_f32 v157, v128, v129
	ds_read_b64_tr_b16 v[122:123], v200 offset:26624
	ds_read_b64_tr_b16 v[124:125], v200 offset:27136
	s_waitcnt lgkmcnt(13)
	v_mfma_f32_32x32x16_bf16 v[82:97], v[174:177], v[134:137], v[82:97]
	v_add_f32_e32 v195, v100, v195
	v_add_f32_e32 v196, v101, v196
	v_add_f32_e32 v50, v102, v50
	v_add_f32_e32 v194, v103, v194
	v_cvt_pk_bf16_f32 v146, v98, v99
	v_cvt_pk_bf16_f32 v147, v100, v101
	ds_read_b64_tr_b16 v[98:99], v200 offset:30720
	ds_read_b64_tr_b16 v[100:101], v200 offset:31232
	s_waitcnt lgkmcnt(14)
	v_mfma_f32_32x32x16_bf16 v[66:81], v[178:181], v[134:137], v[66:81]
	v_add_f32_e32 v195, v104, v195
	v_add_f32_e32 v196, v105, v196
	v_add_f32_e32 v50, v106, v50
	v_add_f32_e32 v194, v107, v194
	v_cvt_pk_bf16_f32 v148, v102, v103
	v_cvt_pk_bf16_f32 v149, v104, v105
	ds_read_b64_tr_b16 v[102:103], v200 offset:27648
	ds_read_b64_tr_b16 v[104:105], v200 offset:28160
	s_waitcnt lgkmcnt(14)
	v_mfma_f32_32x32x16_bf16 v[82:97], v[182:185], v[130:133], v[82:97]
	v_add_f32_e32 v195, v108, v195
	v_add_f32_e32 v196, v109, v196
	v_add_f32_e32 v50, v110, v50
	v_add_f32_e32 v194, v111, v194
	v_cvt_pk_bf16_f32 v142, v106, v107
	v_cvt_pk_bf16_f32 v143, v108, v109
	ds_read_b64_tr_b16 v[106:107], v200 offset:31744
	ds_read_b64_tr_b16 v[108:109], v200 offset:32256
	v_mfma_f32_32x32x16_bf16 v[66:81], v[52:55], v[130:133], v[66:81]
	v_add_f32_e32 v195, v112, v195
	v_add_f32_e32 v196, v113, v196
	v_cvt_pk_bf16_f32 v144, v110, v111
	v_cvt_pk_bf16_f32 v145, v112, v113
	s_add_i32 s6, s76, s70
	s_mov_b32 s7, m0
	s_mov_b32 m0, s6
	s_nop 0
	global_load_lds_dwordx4 v197, s[98:99]
	s_mov_b32 m0, s7
	s_add_i32 s6, s31, s71
	s_mov_b32 s7, m0
	s_mov_b32 m0, s6
	s_nop 0
	global_load_lds_dwordx4 v197, s[100:101]
	s_mov_b32 m0, s7
	s_add_u32 s98, s98, 0x2000
	s_addc_u32 s99, s99, 0
	s_add_u32 s100, s100, 0x2000
	s_addc_u32 s101, s101, 0
	s_waitcnt lgkmcnt(14)
	v_mfma_f32_32x32x16_bf16 v[2:17], v[158:161], v[186:189], v[2:17]
	v_exp_f32_e32 v82, v82
	v_exp_f32_e32 v83, v83
	v_exp_f32_e32 v84, v84
	v_exp_f32_e32 v85, v85
	s_waitcnt lgkmcnt(12)
	v_mfma_f32_32x32x16_bf16 v[18:33], v[158:161], v[60:63], v[18:33]
	v_exp_f32_e32 v86, v86
	v_exp_f32_e32 v87, v87
	v_exp_f32_e32 v88, v88
	v_exp_f32_e32 v89, v89
	ds_read_b128 v[190:193], v202
	ds_read_b128 v[186:189], v202 offset:512
	s_waitcnt lgkmcnt(12)
	v_mfma_f32_32x32x16_bf16 v[2:17], v[154:157], v[114:117], v[2:17]
	v_exp_f32_e32 v90, v90
	v_exp_f32_e32 v91, v91
	v_exp_f32_e32 v92, v92
	v_exp_f32_e32 v93, v93
	ds_read_b128 v[182:185], v202 offset:2048
	ds_read_b128 v[178:181], v202 offset:2560
	s_waitcnt lgkmcnt(12)
	v_mfma_f32_32x32x16_bf16 v[18:33], v[154:157], v[118:121], v[18:33]
	v_exp_f32_e32 v94, v94
	v_exp_f32_e32 v95, v95
	v_exp_f32_e32 v96, v96
	v_exp_f32_e32 v97, v97
	ds_read_b128 v[174:177], v202 offset:4096
	ds_read_b128 v[170:173], v202 offset:4608
	s_waitcnt lgkmcnt(12)
	v_mfma_f32_32x32x16_bf16 v[2:17], v[146:149], v[122:125], v[2:17]
	v_exp_f32_e32 v66, v66
	v_exp_f32_e32 v67, v67
	v_exp_f32_e32 v68, v68
	v_exp_f32_e32 v69, v69
	ds_read_b128 v[166:169], v202 offset:6144
	ds_read_b128 v[162:165], v202 offset:6656
	s_waitcnt lgkmcnt(12)
	v_mfma_f32_32x32x16_bf16 v[18:33], v[146:149], v[98:101], v[18:33]
	v_exp_f32_e32 v70, v70
	v_exp_f32_e32 v71, v71
	v_exp_f32_e32 v72, v72
	v_exp_f32_e32 v73, v73
	s_waitcnt lgkmcnt(10)
	v_mfma_f32_32x32x16_bf16 v[2:17], v[142:145], v[102:105], v[2:17]
	v_exp_f32_e32 v74, v74
	v_exp_f32_e32 v75, v75
	v_exp_f32_e32 v76, v76
	v_exp_f32_e32 v77, v77
	s_waitcnt lgkmcnt(8)
	v_mfma_f32_32x32x16_bf16 v[18:33], v[142:145], v[106:109], v[18:33]
	v_exp_f32_e32 v78, v78
	v_exp_f32_e32 v79, v79
	v_exp_f32_e32 v80, v80
	v_exp_f32_e32 v81, v81
	s_add_i32 s6, s31, 0x2000
	s_cmpk_lg_i32 s31, 0x4000
	s_mov_b32 s24, s76
	s_cselect_b32 s76, s6, 0
	s_add_i32 s26, s26, 2
	s_cmp_ge_i32 s26, s91
	s_cbranch_scc1 .Lattn_exit
	s_waitcnt vmcnt(2) lgkmcnt(0)
	s_barrier
; #define WAIT_BAR(N) asm volatile("s_waitcnt vmcnt(" #N ") lgkmcnt(0)\n\ts_barrier":::"memory")
;   #define RESC() do{ if(resc){ asm volatile("s_waitcnt lgkmcnt(0)":::"memory"); \
;       _Pragma("unroll") for(int d_=0;d_<2;++d_) _Pragma("unroll") for(int r=0;r<16;++r)o[d_][r]*=wsf[crow(r,hi)]; } }while(0)
;   #define ROT() do{sl_prev=sl_cur;sl_cur=sl_next;sl_next=(sl_next==(NSLOT-1)*SLOTB)?0:sl_next+SLOTB;}while(0)
; template<int THRL> __device__ __forceinline__ void attn_unit(const bf16*Qu,const bf16*__restrict__ Kh,const bf16*__restrict__ Vh,bf16*Ou,const int NT,const float shift,char*shm){
;     ...
;   int t=1;
;     ...
;   for(;t+5<NT;t+=2){
;     STEP(pB0,pB1,pA0,pA1,t,true,true,true);     WAIT_BAR(2); RESC(); ROT();
;     STEP(pA0,pA1,pB0,pB1,t+1,true,true,true);   WAIT_BAR(2); RESC(); ROT();
.Lattn_cpB:
	s_mov_b32 s4, s76
	s_mov_b32 s5, s26
	s_mov_b32 s25, s31
	ds_read_b64_tr_b16 v[52:53], v201 offset:24576
	ds_read_b64_tr_b16 v[54:55], v201 offset:25088
	s_waitcnt lgkmcnt(9)
	v_mfma_f32_32x32x16_bf16 v[114:129], v[190:193], v[150:153], v[34:49]
	v_add_f32_e32 v50, v82, v50
	v_add_f32_e32 v194, v83, v194
	v_add_f32_e32 v195, v84, v195
	v_add_f32_e32 v196, v85, v196
	v_add_f32_e32 v50, v86, v50
	v_add_f32_e32 v194, v87, v194
	v_cvt_pk_bf16_f32 v158, v82, v83
	v_cvt_pk_bf16_f32 v159, v84, v85
	ds_read_b64_tr_b16 v[60:61], v201 offset:28672
	ds_read_b64_tr_b16 v[62:63], v201 offset:29184
	s_waitcnt lgkmcnt(10)
	v_mfma_f32_32x32x16_bf16 v[98:113], v[186:189], v[150:153], v[34:49]
	v_add_f32_e32 v195, v88, v195
	v_add_f32_e32 v196, v89, v196
	v_add_f32_e32 v50, v90, v50
	v_add_f32_e32 v194, v91, v194
	v_cvt_pk_bf16_f32 v160, v86, v87
	v_cvt_pk_bf16_f32 v161, v88, v89
	ds_read_b64_tr_b16 v[82:83], v201 offset:25600
	ds_read_b64_tr_b16 v[84:85], v201 offset:26112
	s_waitcnt lgkmcnt(11)
	v_mfma_f32_32x32x16_bf16 v[114:129], v[182:185], v[138:141], v[114:129]
	v_add_f32_e32 v195, v92, v195
	v_add_f32_e32 v196, v93, v196
	v_add_f32_e32 v50, v94, v50
	v_add_f32_e32 v194, v95, v194
	v_cvt_pk_bf16_f32 v154, v90, v91
	v_cvt_pk_bf16_f32 v155, v92, v93
	ds_read_b64_tr_b16 v[86:87], v201 offset:29696
	ds_read_b64_tr_b16 v[88:89], v201 offset:30208
	s_waitcnt lgkmcnt(12)
	v_mfma_f32_32x32x16_bf16 v[98:113], v[178:181], v[138:141], v[98:113]
	v_add_f32_e32 v195, v96, v195
	v_add_f32_e32 v196, v97, v196
	v_add_f32_e32 v50, v66, v50
	v_add_f32_e32 v194, v67, v194
	v_cvt_pk_bf16_f32 v156, v94, v95
	v_cvt_pk_bf16_f32 v157, v96, v97
	ds_read_b64_tr_b16 v[90:91], v201 offset:26624
	ds_read_b64_tr_b16 v[92:93], v201 offset:27136
	s_waitcnt lgkmcnt(13)
	v_mfma_f32_32x32x16_bf16 v[114:129], v[174:177], v[134:137], v[114:129]
	v_add_f32_e32 v195, v68, v195
	v_add_f32_e32 v196, v69, v196
	v_add_f32_e32 v50, v70, v50
	v_add_f32_e32 v194, v71, v194
	v_cvt_pk_bf16_f32 v146, v66, v67
	v_cvt_pk_bf16_f32 v147, v68, v69
	ds_read_b64_tr_b16 v[64:65], v201 offset:30720
	ds_read_b64_tr_b16 v[66:67], v201 offset:31232
	s_waitcnt lgkmcnt(14)
	v_mfma_f32_32x32x16_bf16 v[98:113], v[170:173], v[134:137], v[98:113]
	v_add_f32_e32 v195, v72, v195
	v_add_f32_e32 v196, v73, v196
	v_add_f32_e32 v50, v74, v50
	v_add_f32_e32 v194, v75, v194
	v_cvt_pk_bf16_f32 v148, v70, v71
	v_cvt_pk_bf16_f32 v149, v72, v73
	ds_read_b64_tr_b16 v[68:69], v201 offset:27648
	ds_read_b64_tr_b16 v[70:71], v201 offset:28160
	s_waitcnt lgkmcnt(14)
	v_mfma_f32_32x32x16_bf16 v[114:129], v[166:169], v[130:133], v[114:129]
	v_add_f32_e32 v195, v76, v195
	v_add_f32_e32 v196, v77, v196
	v_add_f32_e32 v50, v78, v50
	v_add_f32_e32 v194, v79, v194
	v_cvt_pk_bf16_f32 v142, v74, v75
	v_cvt_pk_bf16_f32 v143, v76, v77
	ds_read_b64_tr_b16 v[72:73], v201 offset:31744
	ds_read_b64_tr_b16 v[74:75], v201 offset:32256
	v_mfma_f32_32x32x16_bf16 v[98:113], v[162:165], v[130:133], v[98:113]
	v_add_f32_e32 v195, v80, v195
	v_add_f32_e32 v196, v81, v196
	v_cvt_pk_bf16_f32 v144, v78, v79
	v_cvt_pk_bf16_f32 v145, v80, v81
	s_add_i32 s6, s31, s70
	s_mov_b32 s7, m0
	s_mov_b32 m0, s6
	s_nop 0
	global_load_lds_dwordx4 v197, s[98:99]
	s_mov_b32 m0, s7
	s_add_i32 s6, s76, s71
	s_mov_b32 s7, m0
	s_mov_b32 m0, s6
	s_nop 0
	global_load_lds_dwordx4 v197, s[100:101]
	s_mov_b32 m0, s7
	s_add_u32 s98, s98, 0x2000
	s_addc_u32 s99, s99, 0
	s_add_u32 s100, s100, 0x2000
	s_addc_u32 s101, s101, 0
	s_waitcnt lgkmcnt(14)
	v_mfma_f32_32x32x16_bf16 v[2:17], v[158:161], v[52:55], v[2:17]
	v_exp_f32_e32 v114, v114
	v_exp_f32_e32 v115, v115
	v_exp_f32_e32 v116, v116
	v_exp_f32_e32 v117, v117
	s_waitcnt lgkmcnt(12)
	v_mfma_f32_32x32x16_bf16 v[18:33], v[158:161], v[60:63], v[18:33]
	v_exp_f32_e32 v118, v118
	v_exp_f32_e32 v119, v119
	v_exp_f32_e32 v120, v120
	v_exp_f32_e32 v121, v121
	ds_read_b128 v[60:63], v203
	ds_read_b128 v[162:165], v203 offset:512
	s_waitcnt lgkmcnt(12)
	v_mfma_f32_32x32x16_bf16 v[2:17], v[154:157], v[82:85], v[2:17]
	v_exp_f32_e32 v122, v122
	v_exp_f32_e32 v123, v123
	v_exp_f32_e32 v124, v124
	v_exp_f32_e32 v125, v125
	ds_read_b128 v[166:169], v203 offset:2048
	ds_read_b128 v[170:173], v203 offset:2560
	s_waitcnt lgkmcnt(12)
	v_mfma_f32_32x32x16_bf16 v[18:33], v[154:157], v[86:89], v[18:33]
	v_exp_f32_e32 v126, v126
	v_exp_f32_e32 v127, v127
	v_exp_f32_e32 v128, v128
	v_exp_f32_e32 v129, v129
	ds_read_b128 v[174:177], v203 offset:4096
	ds_read_b128 v[178:181], v203 offset:4608
	s_waitcnt lgkmcnt(12)
	v_mfma_f32_32x32x16_bf16 v[2:17], v[146:149], v[90:93], v[2:17]
	v_exp_f32_e32 v98, v98
	v_exp_f32_e32 v99, v99
	v_exp_f32_e32 v100, v100
	v_exp_f32_e32 v101, v101
	ds_read_b128 v[182:185], v203 offset:6144
	ds_read_b128 v[52:55], v203 offset:6656
	s_waitcnt lgkmcnt(12)
	v_mfma_f32_32x32x16_bf16 v[18:33], v[146:149], v[64:67], v[18:33]
	v_exp_f32_e32 v102, v102
	v_exp_f32_e32 v103, v103
	v_exp_f32_e32 v104, v104
	v_exp_f32_e32 v105, v105
	s_waitcnt lgkmcnt(10)
	v_mfma_f32_32x32x16_bf16 v[2:17], v[142:145], v[68:71], v[2:17]
	v_exp_f32_e32 v106, v106
	v_exp_f32_e32 v107, v107
	v_exp_f32_e32 v108, v108
	v_exp_f32_e32 v109, v109
	s_waitcnt lgkmcnt(8)
	v_mfma_f32_32x32x16_bf16 v[18:33], v[142:145], v[72:75], v[18:33]
	v_exp_f32_e32 v110, v110
	v_exp_f32_e32 v111, v111
	v_exp_f32_e32 v112, v112
	v_exp_f32_e32 v113, v113
	s_waitcnt vmcnt(2) lgkmcnt(0)
	s_barrier
; #define WAIT_BAR(N) asm volatile("s_waitcnt vmcnt(" #N ") lgkmcnt(0)\n\ts_barrier":::"memory")
;   #define RESC() do{ if(resc){ asm volatile("s_waitcnt lgkmcnt(0)":::"memory"); \
;       _Pragma("unroll") for(int d_=0;d_<2;++d_) _Pragma("unroll") for(int r=0;r<16;++r)o[d_][r]*=wsf[crow(r,hi)]; } }while(0)
;   #define ROT() do{sl_prev=sl_cur;sl_cur=sl_next;sl_next=(sl_next==(NSLOT-1)*SLOTB)?0:sl_next+SLOTB;}while(0)
; template<int THRL> __device__ __forceinline__ void attn_unit(const bf16*Qu,const bf16*__restrict__ Kh,const bf16*__restrict__ Vh,bf16*Ou,const int NT,const float shift,char*shm){
;     ...
;   int t=1;
;     ...
;   for(;t+5<NT;t+=2){
;     STEP(pB0,pB1,pA0,pA1,t,true,true,true);     WAIT_BAR(2); RESC(); ROT();
;     STEP(pA0,pA1,pB0,pB1,t+1,true,true,true);   WAIT_BAR(2); RESC(); ROT();
;   }
	s_add_i32 s6, s76, 0x2000
	s_cmpk_lg_i32 s76, 0x4000
	s_cselect_b32 s31, s6, 0
	ds_read_b64_tr_b16 v[186:187], v199 offset:24576
	ds_read_b64_tr_b16 v[188:189], v199 offset:25088
	s_waitcnt lgkmcnt(9)
	v_mfma_f32_32x32x16_bf16 v[82:97], v[60:63], v[150:153], v[34:49]
	v_add_f32_e32 v50, v114, v50
	v_add_f32_e32 v194, v115, v194
	v_add_f32_e32 v195, v116, v195
	v_add_f32_e32 v196, v117, v196
	v_add_f32_e32 v50, v118, v50
	v_add_f32_e32 v194, v119, v194
	v_cvt_pk_bf16_f32 v158, v114, v115
	v_cvt_pk_bf16_f32 v159, v116, v117
	ds_read_b64_tr_b16 v[60:61], v199 offset:28672
	ds_read_b64_tr_b16 v[62:63], v199 offset:29184
	s_waitcnt lgkmcnt(10)
	v_mfma_f32_32x32x16_bf16 v[66:81], v[162:165], v[150:153], v[34:49]
	v_add_f32_e32 v195, v120, v195
	v_add_f32_e32 v196, v121, v196
	v_add_f32_e32 v50, v122, v50
	v_add_f32_e32 v194, v123, v194
	v_cvt_pk_bf16_f32 v160, v118, v119
	v_cvt_pk_bf16_f32 v161, v120, v121
	ds_read_b64_tr_b16 v[114:115], v199 offset:25600
	ds_read_b64_tr_b16 v[116:117], v199 offset:26112
	s_waitcnt lgkmcnt(11)
	v_mfma_f32_32x32x16_bf16 v[82:97], v[166:169], v[138:141], v[82:97]
	v_add_f32_e32 v195, v124, v195
	v_add_f32_e32 v196, v125, v196
	v_add_f32_e32 v50, v126, v50
	v_add_f32_e32 v194, v127, v194
	v_cvt_pk_bf16_f32 v154, v122, v123
	v_cvt_pk_bf16_f32 v155, v124, v125
	ds_read_b64_tr_b16 v[118:119], v199 offset:29696
	ds_read_b64_tr_b16 v[120:121], v199 offset:30208
	s_waitcnt lgkmcnt(12)
	v_mfma_f32_32x32x16_bf16 v[66:81], v[170:173], v[138:141], v[66:81]
	v_add_f32_e32 v195, v128, v195
	v_add_f32_e32 v196, v129, v196
	v_add_f32_e32 v50, v98, v50
	v_add_f32_e32 v194, v99, v194
	v_cvt_pk_bf16_f32 v156, v126, v127
	v_cvt_pk_bf16_f32 v157, v128, v129
	ds_read_b64_tr_b16 v[122:123], v199 offset:26624
	ds_read_b64_tr_b16 v[124:125], v199 offset:27136
	s_waitcnt lgkmcnt(13)
	v_mfma_f32_32x32x16_bf16 v[82:97], v[174:177], v[134:137], v[82:97]
	v_add_f32_e32 v195, v100, v195
	v_add_f32_e32 v196, v101, v196
	v_add_f32_e32 v50, v102, v50
	v_add_f32_e32 v194, v103, v194
	v_cvt_pk_bf16_f32 v146, v98, v99
	v_cvt_pk_bf16_f32 v147, v100, v101
	ds_read_b64_tr_b16 v[98:99], v199 offset:30720
	ds_read_b64_tr_b16 v[100:101], v199 offset:31232
	s_waitcnt lgkmcnt(14)
	v_mfma_f32_32x32x16_bf16 v[66:81], v[178:181], v[134:137], v[66:81]
	v_add_f32_e32 v195, v104, v195
	v_add_f32_e32 v196, v105, v196
	v_add_f32_e32 v50, v106, v50
	v_add_f32_e32 v194, v107, v194
	v_cvt_pk_bf16_f32 v148, v102, v103
	v_cvt_pk_bf16_f32 v149, v104, v105
	ds_read_b64_tr_b16 v[102:103], v199 offset:27648
	ds_read_b64_tr_b16 v[104:105], v199 offset:28160
	s_waitcnt lgkmcnt(14)
	v_mfma_f32_32x32x16_bf16 v[82:97], v[182:185], v[130:133], v[82:97]
	v_add_f32_e32 v195, v108, v195
	v_add_f32_e32 v196, v109, v196
	v_add_f32_e32 v50, v110, v50
	v_add_f32_e32 v194, v111, v194
	v_cvt_pk_bf16_f32 v142, v106, v107
	v_cvt_pk_bf16_f32 v143, v108, v109
	ds_read_b64_tr_b16 v[106:107], v199 offset:31744
	ds_read_b64_tr_b16 v[108:109], v199 offset:32256
	v_mfma_f32_32x32x16_bf16 v[66:81], v[52:55], v[130:133], v[66:81]
	v_add_f32_e32 v195, v112, v195
	v_add_f32_e32 v196, v113, v196
	v_cvt_pk_bf16_f32 v144, v110, v111
	v_cvt_pk_bf16_f32 v145, v112, v113
	s_add_i32 s6, s76, s70
	s_mov_b32 s7, m0
	s_mov_b32 m0, s6
	s_nop 0
	global_load_lds_dwordx4 v197, s[98:99]
	s_mov_b32 m0, s7
	s_add_i32 s6, s31, s71
	s_mov_b32 s7, m0
	s_mov_b32 m0, s6
	s_nop 0
	global_load_lds_dwordx4 v197, s[100:101]
	s_mov_b32 m0, s7
	s_add_u32 s98, s98, 0x2000
	s_addc_u32 s99, s99, 0
	s_add_u32 s100, s100, 0x2000
	s_addc_u32 s101, s101, 0
	s_waitcnt lgkmcnt(14)
	v_mfma_f32_32x32x16_bf16 v[2:17], v[158:161], v[186:189], v[2:17]
	v_exp_f32_e32 v82, v82
	v_exp_f32_e32 v83, v83
	v_exp_f32_e32 v84, v84
	v_exp_f32_e32 v85, v85
	s_waitcnt lgkmcnt(12)
	v_mfma_f32_32x32x16_bf16 v[18:33], v[158:161], v[60:63], v[18:33]
	v_exp_f32_e32 v86, v86
	v_exp_f32_e32 v87, v87
	v_exp_f32_e32 v88, v88
	v_exp_f32_e32 v89, v89
	ds_read_b128 v[190:193], v204
	ds_read_b128 v[186:189], v204 offset:512
	s_waitcnt lgkmcnt(12)
	v_mfma_f32_32x32x16_bf16 v[2:17], v[154:157], v[114:117], v[2:17]
	v_exp_f32_e32 v90, v90
	v_exp_f32_e32 v91, v91
	v_exp_f32_e32 v92, v92
	v_exp_f32_e32 v93, v93
	ds_read_b128 v[182:185], v204 offset:2048
	ds_read_b128 v[178:181], v204 offset:2560
	s_waitcnt lgkmcnt(12)
	v_mfma_f32_32x32x16_bf16 v[18:33], v[154:157], v[118:121], v[18:33]
	v_exp_f32_e32 v94, v94
	v_exp_f32_e32 v95, v95
	v_exp_f32_e32 v96, v96
	v_exp_f32_e32 v97, v97
	ds_read_b128 v[174:177], v204 offset:4096
	ds_read_b128 v[170:173], v204 offset:4608
	s_waitcnt lgkmcnt(12)
	v_mfma_f32_32x32x16_bf16 v[2:17], v[146:149], v[122:125], v[2:17]
	v_exp_f32_e32 v66, v66
	v_exp_f32_e32 v67, v67
	v_exp_f32_e32 v68, v68
	v_exp_f32_e32 v69, v69
	ds_read_b128 v[166:169], v204 offset:6144
	ds_read_b128 v[162:165], v204 offset:6656
	s_waitcnt lgkmcnt(12)
	v_mfma_f32_32x32x16_bf16 v[18:33], v[146:149], v[98:101], v[18:33]
	v_exp_f32_e32 v70, v70
	v_exp_f32_e32 v71, v71
	v_exp_f32_e32 v72, v72
	v_exp_f32_e32 v73, v73
	s_waitcnt lgkmcnt(10)
	v_mfma_f32_32x32x16_bf16 v[2:17], v[142:145], v[102:105], v[2:17]
	v_exp_f32_e32 v74, v74
	v_exp_f32_e32 v75, v75
	v_exp_f32_e32 v76, v76
	v_exp_f32_e32 v77, v77
	s_waitcnt lgkmcnt(8)
	v_mfma_f32_32x32x16_bf16 v[18:33], v[142:145], v[106:109], v[18:33]
	v_exp_f32_e32 v78, v78
	v_exp_f32_e32 v79, v79
	v_exp_f32_e32 v80, v80
	v_exp_f32_e32 v81, v81
	s_add_i32 s6, s31, 0x2000
	s_cmpk_lg_i32 s31, 0x4000
	s_mov_b32 s24, s76
	s_cselect_b32 s76, s6, 0
	s_add_i32 s26, s26, 2
	s_cmp_ge_i32 s26, s91
	s_cbranch_scc1 .Lattn_exit
	s_waitcnt vmcnt(2) lgkmcnt(0)
	s_barrier
; #define WAIT_BAR(N) asm volatile("s_waitcnt vmcnt(" #N ") lgkmcnt(0)\n\ts_barrier":::"memory")
;   #define RESC() do{ if(resc){ asm volatile("s_waitcnt lgkmcnt(0)":::"memory"); \
;       _Pragma("unroll") for(int d_=0;d_<2;++d_) _Pragma("unroll") for(int r=0;r<16;++r)o[d_][r]*=wsf[crow(r,hi)]; } }while(0)
;   #define ROT() do{sl_prev=sl_cur;sl_cur=sl_next;sl_next=(sl_next==(NSLOT-1)*SLOTB)?0:sl_next+SLOTB;}while(0)
; template<int THRL> __device__ __forceinline__ void attn_unit(const bf16*Qu,const bf16*__restrict__ Kh,const bf16*__restrict__ Vh,bf16*Ou,const int NT,const float shift,char*shm){
;     ...
;   int t=1;
;     ...
;   for(;t+5<NT;t+=2){
;     STEP(pB0,pB1,pA0,pA1,t,true,true,true);     WAIT_BAR(2); RESC(); ROT();
;     STEP(pA0,pA1,pB0,pB1,t+1,true,true,true);   WAIT_BAR(2); RESC(); ROT();
.Lattn_cpC:
	s_mov_b32 s4, s76
	s_mov_b32 s5, s26
	s_mov_b32 s25, s31
	ds_read_b64_tr_b16 v[52:53], v200 offset:24576
	ds_read_b64_tr_b16 v[54:55], v200 offset:25088
	s_waitcnt lgkmcnt(9)
	v_mfma_f32_32x32x16_bf16 v[114:129], v[190:193], v[150:153], v[34:49]
	v_add_f32_e32 v50, v82, v50
	v_add_f32_e32 v194, v83, v194
	v_add_f32_e32 v195, v84, v195
	v_add_f32_e32 v196, v85, v196
	v_add_f32_e32 v50, v86, v50
	v_add_f32_e32 v194, v87, v194
	v_cvt_pk_bf16_f32 v158, v82, v83
	v_cvt_pk_bf16_f32 v159, v84, v85
	ds_read_b64_tr_b16 v[60:61], v200 offset:28672
	ds_read_b64_tr_b16 v[62:63], v200 offset:29184
	s_waitcnt lgkmcnt(10)
	v_mfma_f32_32x32x16_bf16 v[98:113], v[186:189], v[150:153], v[34:49]
	v_add_f32_e32 v195, v88, v195
	v_add_f32_e32 v196, v89, v196
	v_add_f32_e32 v50, v90, v50
	v_add_f32_e32 v194, v91, v194
	v_cvt_pk_bf16_f32 v160, v86, v87
	v_cvt_pk_bf16_f32 v161, v88, v89
	ds_read_b64_tr_b16 v[82:83], v200 offset:25600
	ds_read_b64_tr_b16 v[84:85], v200 offset:26112
	s_waitcnt lgkmcnt(11)
	v_mfma_f32_32x32x16_bf16 v[114:129], v[182:185], v[138:141], v[114:129]
	v_add_f32_e32 v195, v92, v195
	v_add_f32_e32 v196, v93, v196
	v_add_f32_e32 v50, v94, v50
	v_add_f32_e32 v194, v95, v194
	v_cvt_pk_bf16_f32 v154, v90, v91
	v_cvt_pk_bf16_f32 v155, v92, v93
	ds_read_b64_tr_b16 v[86:87], v200 offset:29696
	ds_read_b64_tr_b16 v[88:89], v200 offset:30208
	s_waitcnt lgkmcnt(12)
	v_mfma_f32_32x32x16_bf16 v[98:113], v[178:181], v[138:141], v[98:113]
	v_add_f32_e32 v195, v96, v195
	v_add_f32_e32 v196, v97, v196
	v_add_f32_e32 v50, v66, v50
	v_add_f32_e32 v194, v67, v194
	v_cvt_pk_bf16_f32 v156, v94, v95
	v_cvt_pk_bf16_f32 v157, v96, v97
	ds_read_b64_tr_b16 v[90:91], v200 offset:26624
	ds_read_b64_tr_b16 v[92:93], v200 offset:27136
	s_waitcnt lgkmcnt(13)
	v_mfma_f32_32x32x16_bf16 v[114:129], v[174:177], v[134:137], v[114:129]
	v_add_f32_e32 v195, v68, v195
	v_add_f32_e32 v196, v69, v196
	v_add_f32_e32 v50, v70, v50
	v_add_f32_e32 v194, v71, v194
	v_cvt_pk_bf16_f32 v146, v66, v67
	v_cvt_pk_bf16_f32 v147, v68, v69
	ds_read_b64_tr_b16 v[64:65], v200 offset:30720
	ds_read_b64_tr_b16 v[66:67], v200 offset:31232
	s_waitcnt lgkmcnt(14)
	v_mfma_f32_32x32x16_bf16 v[98:113], v[170:173], v[134:137], v[98:113]
	v_add_f32_e32 v195, v72, v195
	v_add_f32_e32 v196, v73, v196
	v_add_f32_e32 v50, v74, v50
	v_add_f32_e32 v194, v75, v194
	v_cvt_pk_bf16_f32 v148, v70, v71
	v_cvt_pk_bf16_f32 v149, v72, v73
	ds_read_b64_tr_b16 v[68:69], v200 offset:27648
	ds_read_b64_tr_b16 v[70:71], v200 offset:28160
	s_waitcnt lgkmcnt(14)
	v_mfma_f32_32x32x16_bf16 v[114:129], v[166:169], v[130:133], v[114:129]
	v_add_f32_e32 v195, v76, v195
	v_add_f32_e32 v196, v77, v196
	v_add_f32_e32 v50, v78, v50
	v_add_f32_e32 v194, v79, v194
	v_cvt_pk_bf16_f32 v142, v74, v75
	v_cvt_pk_bf16_f32 v143, v76, v77
	ds_read_b64_tr_b16 v[72:73], v200 offset:31744
	ds_read_b64_tr_b16 v[74:75], v200 offset:32256
	v_mfma_f32_32x32x16_bf16 v[98:113], v[162:165], v[130:133], v[98:113]
	v_add_f32_e32 v195, v80, v195
	v_add_f32_e32 v196, v81, v196
	v_cvt_pk_bf16_f32 v144, v78, v79
	v_cvt_pk_bf16_f32 v145, v80, v81
	s_add_i32 s6, s31, s70
	s_mov_b32 s7, m0
	s_mov_b32 m0, s6
	s_nop 0
	global_load_lds_dwordx4 v197, s[98:99]
	s_mov_b32 m0, s7
	s_add_i32 s6, s76, s71
	s_mov_b32 s7, m0
	s_mov_b32 m0, s6
	s_nop 0
	global_load_lds_dwordx4 v197, s[100:101]
	s_mov_b32 m0, s7
	s_add_u32 s98, s98, 0x2000
	s_addc_u32 s99, s99, 0
	s_add_u32 s100, s100, 0x2000
	s_addc_u32 s101, s101, 0
	s_waitcnt lgkmcnt(14)
	v_mfma_f32_32x32x16_bf16 v[2:17], v[158:161], v[52:55], v[2:17]
	v_exp_f32_e32 v114, v114
	v_exp_f32_e32 v115, v115
	v_exp_f32_e32 v116, v116
	v_exp_f32_e32 v117, v117
	s_waitcnt lgkmcnt(12)
	v_mfma_f32_32x32x16_bf16 v[18:33], v[158:161], v[60:63], v[18:33]
	v_exp_f32_e32 v118, v118
	v_exp_f32_e32 v119, v119
	v_exp_f32_e32 v120, v120
	v_exp_f32_e32 v121, v121
	ds_read_b128 v[60:63], v202
	ds_read_b128 v[162:165], v202 offset:512
	s_waitcnt lgkmcnt(12)
	v_mfma_f32_32x32x16_bf16 v[2:17], v[154:157], v[82:85], v[2:17]
	v_exp_f32_e32 v122, v122
	v_exp_f32_e32 v123, v123
	v_exp_f32_e32 v124, v124
	v_exp_f32_e32 v125, v125
	ds_read_b128 v[166:169], v202 offset:2048
	ds_read_b128 v[170:173], v202 offset:2560
	s_waitcnt lgkmcnt(12)
	v_mfma_f32_32x32x16_bf16 v[18:33], v[154:157], v[86:89], v[18:33]
	v_exp_f32_e32 v126, v126
	v_exp_f32_e32 v127, v127
	v_exp_f32_e32 v128, v128
	v_exp_f32_e32 v129, v129
	ds_read_b128 v[174:177], v202 offset:4096
	ds_read_b128 v[178:181], v202 offset:4608
	s_waitcnt lgkmcnt(12)
	v_mfma_f32_32x32x16_bf16 v[2:17], v[146:149], v[90:93], v[2:17]
	v_exp_f32_e32 v98, v98
	v_exp_f32_e32 v99, v99
	v_exp_f32_e32 v100, v100
	v_exp_f32_e32 v101, v101
	ds_read_b128 v[182:185], v202 offset:6144
	ds_read_b128 v[52:55], v202 offset:6656
	s_waitcnt lgkmcnt(12)
	v_mfma_f32_32x32x16_bf16 v[18:33], v[146:149], v[64:67], v[18:33]
	v_exp_f32_e32 v102, v102
	v_exp_f32_e32 v103, v103
	v_exp_f32_e32 v104, v104
	v_exp_f32_e32 v105, v105
	s_waitcnt lgkmcnt(10)
	v_mfma_f32_32x32x16_bf16 v[2:17], v[142:145], v[68:71], v[2:17]
	v_exp_f32_e32 v106, v106
	v_exp_f32_e32 v107, v107
	v_exp_f32_e32 v108, v108
	v_exp_f32_e32 v109, v109
	s_waitcnt lgkmcnt(8)
	v_mfma_f32_32x32x16_bf16 v[18:33], v[142:145], v[72:75], v[18:33]
	v_exp_f32_e32 v110, v110
	v_exp_f32_e32 v111, v111
	v_exp_f32_e32 v112, v112
	v_exp_f32_e32 v113, v113
	s_waitcnt vmcnt(2) lgkmcnt(0)
	s_barrier
; #define WAIT_BAR(N) asm volatile("s_waitcnt vmcnt(" #N ") lgkmcnt(0)\n\ts_barrier":::"memory")
;   #define RESC() do{ if(resc){ asm volatile("s_waitcnt lgkmcnt(0)":::"memory"); \
;       _Pragma("unroll") for(int d_=0;d_<2;++d_) _Pragma("unroll") for(int r=0;r<16;++r)o[d_][r]*=wsf[crow(r,hi)]; } }while(0)
;   #define ROT() do{sl_prev=sl_cur;sl_cur=sl_next;sl_next=(sl_next==(NSLOT-1)*SLOTB)?0:sl_next+SLOTB;}while(0)
; template<int THRL> __device__ __forceinline__ void attn_unit(const bf16*Qu,const bf16*__restrict__ Kh,const bf16*__restrict__ Vh,bf16*Ou,const int NT,const float shift,char*shm){
;     ...
;   int t=1;
;     ...
;   for(;t+5<NT;t+=2){
;     STEP(pB0,pB1,pA0,pA1,t,true,true,true);     WAIT_BAR(2); RESC(); ROT();
;     STEP(pA0,pA1,pB0,pB1,t+1,true,true,true);   WAIT_BAR(2); RESC(); ROT();
;   }
	s_add_i32 s6, s76, 0x2000
	s_cmpk_lg_i32 s76, 0x4000
	s_cselect_b32 s31, s6, 0
	ds_read_b64_tr_b16 v[186:187], v201 offset:24576
	ds_read_b64_tr_b16 v[188:189], v201 offset:25088
	s_waitcnt lgkmcnt(9)
	v_mfma_f32_32x32x16_bf16 v[82:97], v[60:63], v[150:153], v[34:49]
	v_add_f32_e32 v50, v114, v50
	v_add_f32_e32 v194, v115, v194
	v_add_f32_e32 v195, v116, v195
	v_add_f32_e32 v196, v117, v196
	v_add_f32_e32 v50, v118, v50
	v_add_f32_e32 v194, v119, v194
	v_cvt_pk_bf16_f32 v158, v114, v115
	v_cvt_pk_bf16_f32 v159, v116, v117
	ds_read_b64_tr_b16 v[60:61], v201 offset:28672
	ds_read_b64_tr_b16 v[62:63], v201 offset:29184
	s_waitcnt lgkmcnt(10)
	v_mfma_f32_32x32x16_bf16 v[66:81], v[162:165], v[150:153], v[34:49]
	v_add_f32_e32 v195, v120, v195
	v_add_f32_e32 v196, v121, v196
	v_add_f32_e32 v50, v122, v50
	v_add_f32_e32 v194, v123, v194
	v_cvt_pk_bf16_f32 v160, v118, v119
	v_cvt_pk_bf16_f32 v161, v120, v121
	ds_read_b64_tr_b16 v[114:115], v201 offset:25600
	ds_read_b64_tr_b16 v[116:117], v201 offset:26112
	s_waitcnt lgkmcnt(11)
	v_mfma_f32_32x32x16_bf16 v[82:97], v[166:169], v[138:141], v[82:97]
	v_add_f32_e32 v195, v124, v195
	v_add_f32_e32 v196, v125, v196
	v_add_f32_e32 v50, v126, v50
	v_add_f32_e32 v194, v127, v194
	v_cvt_pk_bf16_f32 v154, v122, v123
	v_cvt_pk_bf16_f32 v155, v124, v125
	ds_read_b64_tr_b16 v[118:119], v201 offset:29696
	ds_read_b64_tr_b16 v[120:121], v201 offset:30208
	s_waitcnt lgkmcnt(12)
	v_mfma_f32_32x32x16_bf16 v[66:81], v[170:173], v[138:141], v[66:81]
	v_add_f32_e32 v195, v128, v195
	v_add_f32_e32 v196, v129, v196
	v_add_f32_e32 v50, v98, v50
	v_add_f32_e32 v194, v99, v194
	v_cvt_pk_bf16_f32 v156, v126, v127
	v_cvt_pk_bf16_f32 v157, v128, v129
	ds_read_b64_tr_b16 v[122:123], v201 offset:26624
	ds_read_b64_tr_b16 v[124:125], v201 offset:27136
	s_waitcnt lgkmcnt(13)
	v_mfma_f32_32x32x16_bf16 v[82:97], v[174:177], v[134:137], v[82:97]
	v_add_f32_e32 v195, v100, v195
	v_add_f32_e32 v196, v101, v196
	v_add_f32_e32 v50, v102, v50
	v_add_f32_e32 v194, v103, v194
	v_cvt_pk_bf16_f32 v146, v98, v99
	v_cvt_pk_bf16_f32 v147, v100, v101
	ds_read_b64_tr_b16 v[98:99], v201 offset:30720
	ds_read_b64_tr_b16 v[100:101], v201 offset:31232
	s_waitcnt lgkmcnt(14)
	v_mfma_f32_32x32x16_bf16 v[66:81], v[178:181], v[134:137], v[66:81]
	v_add_f32_e32 v195, v104, v195
	v_add_f32_e32 v196, v105, v196
	v_add_f32_e32 v50, v106, v50
	v_add_f32_e32 v194, v107, v194
	v_cvt_pk_bf16_f32 v148, v102, v103
	v_cvt_pk_bf16_f32 v149, v104, v105
	ds_read_b64_tr_b16 v[102:103], v201 offset:27648
	ds_read_b64_tr_b16 v[104:105], v201 offset:28160
	s_waitcnt lgkmcnt(14)
	v_mfma_f32_32x32x16_bf16 v[82:97], v[182:185], v[130:133], v[82:97]
	v_add_f32_e32 v195, v108, v195
	v_add_f32_e32 v196, v109, v196
	v_add_f32_e32 v50, v110, v50
	v_add_f32_e32 v194, v111, v194
	v_cvt_pk_bf16_f32 v142, v106, v107
	v_cvt_pk_bf16_f32 v143, v108, v109
	ds_read_b64_tr_b16 v[106:107], v201 offset:31744
	ds_read_b64_tr_b16 v[108:109], v201 offset:32256
	v_mfma_f32_32x32x16_bf16 v[66:81], v[52:55], v[130:133], v[66:81]
	v_add_f32_e32 v195, v112, v195
	v_add_f32_e32 v196, v113, v196
	v_cvt_pk_bf16_f32 v144, v110, v111
	v_cvt_pk_bf16_f32 v145, v112, v113
	s_add_i32 s6, s76, s70
	s_mov_b32 s7, m0
	s_mov_b32 m0, s6
	s_nop 0
	global_load_lds_dwordx4 v197, s[98:99]
	s_mov_b32 m0, s7
	s_add_i32 s6, s31, s71
	s_mov_b32 s7, m0
	s_mov_b32 m0, s6
	s_nop 0
	global_load_lds_dwordx4 v197, s[100:101]
	s_mov_b32 m0, s7
	s_add_u32 s98, s98, 0x2000
	s_addc_u32 s99, s99, 0
	s_add_u32 s100, s100, 0x2000
	s_addc_u32 s101, s101, 0
	s_waitcnt lgkmcnt(14)
	v_mfma_f32_32x32x16_bf16 v[2:17], v[158:161], v[186:189], v[2:17]
	v_exp_f32_e32 v82, v82
	v_exp_f32_e32 v83, v83
	v_exp_f32_e32 v84, v84
	v_exp_f32_e32 v85, v85
	s_waitcnt lgkmcnt(12)
	v_mfma_f32_32x32x16_bf16 v[18:33], v[158:161], v[60:63], v[18:33]
	v_exp_f32_e32 v86, v86
	v_exp_f32_e32 v87, v87
	v_exp_f32_e32 v88, v88
	v_exp_f32_e32 v89, v89
	ds_read_b128 v[190:193], v203
	ds_read_b128 v[186:189], v203 offset:512
	s_waitcnt lgkmcnt(12)
	v_mfma_f32_32x32x16_bf16 v[2:17], v[154:157], v[114:117], v[2:17]
	v_exp_f32_e32 v90, v90
	v_exp_f32_e32 v91, v91
	v_exp_f32_e32 v92, v92
	v_exp_f32_e32 v93, v93
	ds_read_b128 v[182:185], v203 offset:2048
	ds_read_b128 v[178:181], v203 offset:2560
	s_waitcnt lgkmcnt(12)
	v_mfma_f32_32x32x16_bf16 v[18:33], v[154:157], v[118:121], v[18:33]
	v_exp_f32_e32 v94, v94
	v_exp_f32_e32 v95, v95
	v_exp_f32_e32 v96, v96
	v_exp_f32_e32 v97, v97
	ds_read_b128 v[174:177], v203 offset:4096
	ds_read_b128 v[170:173], v203 offset:4608
	s_waitcnt lgkmcnt(12)
	v_mfma_f32_32x32x16_bf16 v[2:17], v[146:149], v[122:125], v[2:17]
	v_exp_f32_e32 v66, v66
	v_exp_f32_e32 v67, v67
	v_exp_f32_e32 v68, v68
	v_exp_f32_e32 v69, v69
	ds_read_b128 v[166:169], v203 offset:6144
	ds_read_b128 v[162:165], v203 offset:6656
	s_waitcnt lgkmcnt(12)
	v_mfma_f32_32x32x16_bf16 v[18:33], v[146:149], v[98:101], v[18:33]
	v_exp_f32_e32 v70, v70
	v_exp_f32_e32 v71, v71
	v_exp_f32_e32 v72, v72
	v_exp_f32_e32 v73, v73
	s_waitcnt lgkmcnt(10)
	v_mfma_f32_32x32x16_bf16 v[2:17], v[142:145], v[102:105], v[2:17]
	v_exp_f32_e32 v74, v74
	v_exp_f32_e32 v75, v75
	v_exp_f32_e32 v76, v76
	v_exp_f32_e32 v77, v77
	s_waitcnt lgkmcnt(8)
	v_mfma_f32_32x32x16_bf16 v[18:33], v[142:145], v[106:109], v[18:33]
	v_exp_f32_e32 v78, v78
	v_exp_f32_e32 v79, v79
	v_exp_f32_e32 v80, v80
	v_exp_f32_e32 v81, v81
	s_add_i32 s6, s31, 0x2000
	s_cmpk_lg_i32 s31, 0x4000
	s_mov_b32 s24, s76
	s_cselect_b32 s76, s6, 0
	s_add_i32 s26, s26, 2
	s_cmp_ge_i32 s26, s91
	s_cbranch_scc0 .Lattn_rot
.Lattn_exit:
	s_waitcnt vmcnt(2) lgkmcnt(0)
	s_barrier
	v_add_f32_e32 v50, v50, v194
	v_add_f32_e32 v50, v50, v195
	v_add_f32_e32 v50, v50, v196
	s_add_i32 s5, s5, -3
	s_branch .LBB0_621
